# HGRN unit: one barrier per chunk (cumulative sums of chunk c+2 at the end of the interval, double-buffered totals and output staging), counted vmcnt so the q2 stores are not waited for
# baseline (speedup 1.0000x reference)
.Lhg_w01_1:
	v_add_f32_e32 v24, v24, v205
	s_waitcnt vmcnt(8)
	v_mov_b32_e32 v68, v60
	v_add_f32_e32 v69, v68, v61
	v_add_f32_e32 v70, v69, v62
	v_add_f32_e32 v71, v70, v63
	v_add_f32_e32 v72, v71, v64
	v_add_f32_e32 v73, v72, v65
	v_add_f32_e32 v74, v73, v66
	v_add_f32_e32 v75, v74, v67
	ds_write_b32 v1, v75 offset:2048
	s_waitcnt lgkmcnt(0)
	s_barrier
	v_xor_b32_e32 v2, 0x10000, v2
	v_xor_b32_e32 v4, 0x10000, v4
	v_xor_b32_e32 v26, 0x10000, v26
	s_mov_b32 s28, 0
.Lhg_loop:
	s_cmp_gt_u32 s28, 29
	s_cbranch_scc1 .Lhg_noload_2
	global_load_dword v28, v14, s[4:5]
	global_load_dword v29, v14, s[4:5] offset:3072
	global_load_dword v30, v15, s[4:5]
	global_load_dword v31, v15, s[4:5] offset:3072
	global_load_dword v32, v16, s[4:5]
	global_load_dword v33, v16, s[4:5] offset:3072
	global_load_dword v34, v17, s[4:5]
	global_load_dword v35, v17, s[4:5] offset:3072
	global_load_ushort v44, v18, s[8:9]
	global_load_ushort v45, v18, s[8:9] offset:1536
	global_load_ushort v46, v18, s[8:9] offset:3072
	global_load_ushort v47, v19, s[8:9]
	global_load_ushort v48, v19, s[8:9] offset:1536
	global_load_ushort v49, v19, s[8:9] offset:3072
	global_load_ushort v50, v20, s[8:9]
	global_load_ushort v51, v20, s[8:9] offset:1536
	global_load_ushort v52, v18, s[10:11]
	global_load_ushort v53, v18, s[10:11] offset:1536
	global_load_ushort v54, v18, s[10:11] offset:3072
	global_load_ushort v55, v19, s[10:11]
	global_load_ushort v56, v19, s[10:11] offset:1536
	global_load_ushort v57, v19, s[10:11] offset:3072
	global_load_ushort v58, v20, s[10:11]
	global_load_ushort v59, v20, s[10:11] offset:1536
	s_add_u32 s4, s4, 0x18000
	s_addc_u32 s5, s5, 0
	s_add_u32 s8, s8, 0xc000
	s_addc_u32 s9, s9, 0
	s_add_u32 s10, s10, 0xc000
	s_addc_u32 s11, s11, 0
.Lhg_noload_2:
	s_cmp_gt_u32 s18, 3
	s_cbranch_scc1 .Lhg_bfirst_3
	ds_read_b128 v[144:147], v5 offset:8704
	ds_read_b128 v[148:151], v5 offset:13056
	ds_read_b128 v[152:155], v5 offset:0
	ds_read_b128 v[172:175], v5 offset:4352
	ds_read_b128 v[176:179], v5 offset:8768
	ds_read_b128 v[180:183], v5 offset:13120
	ds_read_b128 v[184:187], v5 offset:64
	ds_read_b128 v[188:191], v5 offset:4416
	s_waitcnt lgkmcnt(4)
	v_mfma_f32_16x16x32_bf16 v[124:127], v[144:147], v[152:155], 0
	v_mfma_f32_16x16x32_bf16 v[128:131], v[144:147], v[172:175], 0
	v_mfma_f32_16x16x32_bf16 v[132:135], v[148:151], v[172:175], 0
	ds_read_b128 v[144:147], v5 offset:8832
	ds_read_b128 v[148:151], v5 offset:13184
	ds_read_b128 v[152:155], v5 offset:128
	ds_read_b128 v[172:175], v5 offset:4480
	s_waitcnt lgkmcnt(4)
	v_mfma_f32_16x16x32_bf16 v[124:127], v[176:179], v[184:187], v[124:127]
	v_mfma_f32_16x16x32_bf16 v[128:131], v[176:179], v[188:191], v[128:131]
	v_mfma_f32_16x16x32_bf16 v[132:135], v[180:183], v[188:191], v[132:135]
	ds_read_b128 v[176:179], v5 offset:8896
	ds_read_b128 v[180:183], v5 offset:13248
	ds_read_b128 v[184:187], v5 offset:192
	ds_read_b128 v[188:191], v5 offset:4544
	s_waitcnt lgkmcnt(4)
	v_mfma_f32_16x16x32_bf16 v[124:127], v[144:147], v[152:155], v[124:127]
	v_mfma_f32_16x16x32_bf16 v[128:131], v[144:147], v[172:175], v[128:131]
	v_mfma_f32_16x16x32_bf16 v[132:135], v[148:151], v[172:175], v[132:135]
	s_waitcnt lgkmcnt(0)
	v_mfma_f32_16x16x32_bf16 v[124:127], v[176:179], v[184:187], v[124:127]
	v_mfma_f32_16x16x32_bf16 v[128:131], v[176:179], v[188:191], v[128:131]
	v_mfma_f32_16x16x32_bf16 v[132:135], v[180:183], v[188:191], v[132:135]
	ds_read_b64 v[204:205], v6
	ds_read_b64 v[206:207], v6 offset:32
	ds_read_b64 v[208:209], v6 offset:4352
	ds_read_b64 v[210:211], v6 offset:4384
	v_cvt_pk_bf16_f32 v200, v92, v93
	v_cvt_pk_bf16_f32 v201, v94, v95
	v_cvt_pk_bf16_f32 v202, v96, v97
	v_cvt_pk_bf16_f32 v203, v98, v99
	s_waitcnt lgkmcnt(0)
	s_nop 1
	v_mfma_f32_16x16x32_bf16 v[136:139], v[204:207], v[200:203], 0
	v_mfma_f32_16x16x32_bf16 v[140:143], v[208:211], v[200:203], 0
	ds_read_b64 v[204:205], v6 offset:64
	ds_read_b64 v[206:207], v6 offset:96
	ds_read_b64 v[208:209], v6 offset:4416
	ds_read_b64 v[210:211], v6 offset:4448
	v_cvt_pk_bf16_f32 v200, v100, v101
	v_cvt_pk_bf16_f32 v201, v102, v103
	v_cvt_pk_bf16_f32 v202, v104, v105
	v_cvt_pk_bf16_f32 v203, v106, v107
	s_waitcnt lgkmcnt(0)
	s_nop 1
	v_mfma_f32_16x16x32_bf16 v[136:139], v[204:207], v[200:203], v[136:139]
	v_mfma_f32_16x16x32_bf16 v[140:143], v[208:211], v[200:203], v[140:143]
	ds_read_b64 v[204:205], v6 offset:128
	ds_read_b64 v[206:207], v6 offset:160
	ds_read_b64 v[208:209], v6 offset:4480
	ds_read_b64 v[210:211], v6 offset:4512
	v_cvt_pk_bf16_f32 v200, v108, v109
	v_cvt_pk_bf16_f32 v201, v110, v111
	v_cvt_pk_bf16_f32 v202, v112, v113
	v_cvt_pk_bf16_f32 v203, v114, v115
	s_waitcnt lgkmcnt(0)
	s_nop 1
	v_mfma_f32_16x16x32_bf16 v[136:139], v[204:207], v[200:203], v[136:139]
	v_mfma_f32_16x16x32_bf16 v[140:143], v[208:211], v[200:203], v[140:143]
	ds_read_b64 v[204:205], v6 offset:192
	ds_read_b64 v[206:207], v6 offset:224
	ds_read_b64 v[208:209], v6 offset:4544
	ds_read_b64 v[210:211], v6 offset:4576
	v_cvt_pk_bf16_f32 v200, v116, v117
	v_cvt_pk_bf16_f32 v201, v118, v119
	v_cvt_pk_bf16_f32 v202, v120, v121
	v_cvt_pk_bf16_f32 v203, v122, v123
	s_waitcnt lgkmcnt(0)
	s_nop 1
	v_mfma_f32_16x16x32_bf16 v[136:139], v[204:207], v[200:203], v[136:139]
	v_mfma_f32_16x16x32_bf16 v[140:143], v[208:211], v[200:203], v[140:143]
	ds_read_b64 v[212:213], v7 offset:27648
	ds_read_b64 v[214:215], v7 offset:27680
	ds_read_b128 v[216:219], v8 offset:27648
	v_cndmask_b32_e64 v124, 0, v124, s[40:41]
	v_cndmask_b32_e64 v132, 0, v132, s[40:41]
	v_cndmask_b32_e64 v125, 0, v125, s[42:43]
	v_cndmask_b32_e64 v133, 0, v133, s[42:43]
	v_cndmask_b32_e64 v126, 0, v126, s[44:45]
	v_cndmask_b32_e64 v134, 0, v134, s[44:45]
	v_cndmask_b32_e64 v127, 0, v127, s[46:47]
	v_cndmask_b32_e64 v135, 0, v135, s[46:47]
	v_cvt_pk_bf16_f32 v124, v124, v125
	v_cvt_pk_bf16_f32 v125, v126, v127
	v_mov_b32_e32 v126, 0
	v_mov_b32_e32 v127, 0
	v_cvt_pk_bf16_f32 v128, v128, v129
	v_cvt_pk_bf16_f32 v129, v130, v131
	v_cvt_pk_bf16_f32 v130, v132, v133
	v_cvt_pk_bf16_f32 v131, v134, v135
	s_waitcnt lgkmcnt(0)
	s_nop 1
	v_mfma_f32_16x16x32_bf16 v[136:139], v[124:127], v[212:215], v[136:139]
	v_mfma_f32_16x16x32_bf16 v[140:143], v[128:131], v[212:215], v[140:143]
	ds_read_b128 v[220:223], v9 offset:17408
	ds_read_b128 v[228:231], v10 offset:37888
	ds_read_b128 v[224:227], v9 offset:18688
	ds_read_b128 v[232:235], v10 offset:37952
	s_waitcnt lgkmcnt(2)
	v_pk_mul_f32 v[92:93], v[92:93], v[228:229]
	v_pk_mul_f32 v[94:95], v[94:95], v[230:231]
	s_nop 1
	v_mfma_f32_16x16x32_bf16 v[92:95], v[220:223], v[216:219], v[92:95]
	ds_read_b128 v[220:223], v9 offset:19968
	ds_read_b128 v[228:231], v10 offset:38016
	s_waitcnt lgkmcnt(2)
	v_pk_mul_f32 v[96:97], v[96:97], v[232:233]
	v_pk_mul_f32 v[98:99], v[98:99], v[234:235]
	s_nop 1
	v_mfma_f32_16x16x32_bf16 v[96:99], v[224:227], v[216:219], v[96:99]
	ds_read_b128 v[224:227], v9 offset:21248
	ds_read_b128 v[232:235], v10 offset:38080
	s_waitcnt lgkmcnt(2)
	v_pk_mul_f32 v[100:101], v[100:101], v[228:229]
	v_pk_mul_f32 v[102:103], v[102:103], v[230:231]
	s_nop 1
	v_mfma_f32_16x16x32_bf16 v[100:103], v[220:223], v[216:219], v[100:103]
	ds_read_b128 v[220:223], v9 offset:22528
	ds_read_b128 v[228:231], v10 offset:38144
	s_waitcnt lgkmcnt(2)
	v_pk_mul_f32 v[104:105], v[104:105], v[232:233]
	v_pk_mul_f32 v[106:107], v[106:107], v[234:235]
	s_nop 1
	v_mfma_f32_16x16x32_bf16 v[104:107], v[224:227], v[216:219], v[104:107]
	ds_read_b128 v[224:227], v9 offset:23808
	ds_read_b128 v[232:235], v10 offset:38208
	s_waitcnt lgkmcnt(2)
	v_pk_mul_f32 v[108:109], v[108:109], v[228:229]
	v_pk_mul_f32 v[110:111], v[110:111], v[230:231]
	s_nop 1
	v_mfma_f32_16x16x32_bf16 v[108:111], v[220:223], v[216:219], v[108:111]
	ds_read_b128 v[220:223], v9 offset:25088
	ds_read_b128 v[228:231], v10 offset:38272
	s_waitcnt lgkmcnt(2)
	v_pk_mul_f32 v[112:113], v[112:113], v[232:233]
	v_pk_mul_f32 v[114:115], v[114:115], v[234:235]
	s_nop 1
	v_mfma_f32_16x16x32_bf16 v[112:115], v[224:227], v[216:219], v[112:115]
	ds_read_b128 v[224:227], v9 offset:26368
	ds_read_b128 v[232:235], v10 offset:38336
	s_waitcnt lgkmcnt(2)
	v_pk_mul_f32 v[116:117], v[116:117], v[228:229]
	v_pk_mul_f32 v[118:119], v[118:119], v[230:231]
	s_nop 1
	v_mfma_f32_16x16x32_bf16 v[116:119], v[220:223], v[216:219], v[116:119]
	s_waitcnt lgkmcnt(0)
	v_pk_mul_f32 v[120:121], v[120:121], v[232:233]
	v_pk_mul_f32 v[122:123], v[122:123], v[234:235]
	s_nop 1
	v_mfma_f32_16x16x32_bf16 v[120:123], v[224:227], v[216:219], v[120:123]
	ds_write_b32 v11, v136
	ds_write_b32 v11, v140 offset:8448
	ds_write_b32 v11, v137 offset:528
	ds_write_b32 v11, v141 offset:8976
	ds_write_b32 v11, v138 offset:1056
	ds_write_b32 v11, v142 offset:9504
	ds_write_b32 v11, v139 offset:1584
	ds_write_b32 v11, v143 offset:10032
	ds_read_b32 v200, v0 offset:57344
	ds_read_b32 v201, v0 offset:57856
	ds_read_b32 v202, v0 offset:58368
	ds_read_b32 v203, v0 offset:58880
	v_lshl_or_b32 v220, v85, 16, v84
	v_lshl_or_b32 v221, v87, 16, v86
	v_lshl_or_b32 v222, v89, 16, v88
	v_lshl_or_b32 v223, v91, 16, v90
	ds_write_b128 v4, v[220:223] offset:27648
	s_waitcnt lgkmcnt(1)
	v_mul_f32_e32 v204, v21, v200
	v_fmac_f32_e32 v204, v22, v201
	v_fmac_f32_e32 v204, v23, v202
	v_add_f32_e32 v205, v200, v201
	v_add_f32_e32 v205, v205, v202
	v_add_f32_e32 v205, v205, v203
	v_add_f32_e32 v218, v204, v68
	v_mul_f32_e32 v207, 0x3fb8aa3b, v60
	v_exp_f32_e32 v207, v207
	v_lshlrev_b32_e32 v209, 16, v76
	v_sub_f32_e32 v208, 1.0, v207
	v_mul_f32_e32 v207, 0x3fb8aa3b, v218
	v_exp_f32_e32 v207, v207
	v_add_f32_e32 v206, v218, v24
	v_mul_f32_e32 v224, v209, v207
	v_mul_f32_e32 v206, 0x3fb8aa3b, v206
	v_exp_f32_e32 v206, v206
	v_sub_f32_e32 v207, v205, v218
	v_mul_f32_e32 v60, v209, v206
	v_mul_f32_e32 v207, 0x3fb8aa3b, v207
	v_exp_f32_e32 v207, v207
	v_min_f32_e64 v206, -v218, s29
	v_mul_f32_e32 v210, v208, v207
	v_mul_f32_e32 v206, 0x3fb8aa3b, v206
	v_exp_f32_e32 v206, v206
	s_nop 0
	v_mul_f32_e32 v232, v208, v206
	v_add_f32_e32 v218, v204, v69
	v_mul_f32_e32 v207, 0x3fb8aa3b, v61
	v_exp_f32_e32 v207, v207
	v_lshlrev_b32_e32 v209, 16, v77
	v_sub_f32_e32 v208, 1.0, v207
	v_mul_f32_e32 v207, 0x3fb8aa3b, v218
	v_exp_f32_e32 v207, v207
	v_add_f32_e32 v206, v218, v24
	v_mul_f32_e32 v225, v209, v207
	v_mul_f32_e32 v206, 0x3fb8aa3b, v206
	v_exp_f32_e32 v206, v206
	v_sub_f32_e32 v207, v205, v218
	v_mul_f32_e32 v61, v209, v206
	v_mul_f32_e32 v207, 0x3fb8aa3b, v207
	v_exp_f32_e32 v207, v207
	v_min_f32_e64 v206, -v218, s29
	v_mul_f32_e32 v211, v208, v207
	v_mul_f32_e32 v206, 0x3fb8aa3b, v206
	v_exp_f32_e32 v206, v206
	s_nop 0
	v_mul_f32_e32 v233, v208, v206
	v_add_f32_e32 v218, v204, v70
	v_mul_f32_e32 v207, 0x3fb8aa3b, v62
	v_exp_f32_e32 v207, v207
	v_lshlrev_b32_e32 v209, 16, v78
	v_sub_f32_e32 v208, 1.0, v207
	v_mul_f32_e32 v207, 0x3fb8aa3b, v218
	v_exp_f32_e32 v207, v207
	v_add_f32_e32 v206, v218, v24
	v_mul_f32_e32 v226, v209, v207
	v_mul_f32_e32 v206, 0x3fb8aa3b, v206
	v_exp_f32_e32 v206, v206
	v_sub_f32_e32 v207, v205, v218
	v_mul_f32_e32 v62, v209, v206
	v_mul_f32_e32 v207, 0x3fb8aa3b, v207
	v_exp_f32_e32 v207, v207
	v_min_f32_e64 v206, -v218, s29
	v_mul_f32_e32 v212, v208, v207
	v_mul_f32_e32 v206, 0x3fb8aa3b, v206
	v_exp_f32_e32 v206, v206
	s_nop 0
	v_mul_f32_e32 v234, v208, v206
	v_add_f32_e32 v218, v204, v71
	v_mul_f32_e32 v207, 0x3fb8aa3b, v63
	v_exp_f32_e32 v207, v207
	v_lshlrev_b32_e32 v209, 16, v79
	v_sub_f32_e32 v208, 1.0, v207
	v_mul_f32_e32 v207, 0x3fb8aa3b, v218
	v_exp_f32_e32 v207, v207
	v_add_f32_e32 v206, v218, v24
	v_mul_f32_e32 v227, v209, v207
	v_mul_f32_e32 v206, 0x3fb8aa3b, v206
	v_exp_f32_e32 v206, v206
	v_sub_f32_e32 v207, v205, v218
	v_mul_f32_e32 v63, v209, v206
	v_mul_f32_e32 v207, 0x3fb8aa3b, v207
	v_exp_f32_e32 v207, v207
	v_min_f32_e64 v206, -v218, s29
	v_mul_f32_e32 v213, v208, v207
	v_mul_f32_e32 v206, 0x3fb8aa3b, v206
	v_exp_f32_e32 v206, v206
	s_nop 0
	v_mul_f32_e32 v235, v208, v206
	v_add_f32_e32 v218, v204, v72
	v_mul_f32_e32 v207, 0x3fb8aa3b, v64
	v_exp_f32_e32 v207, v207
	v_lshlrev_b32_e32 v209, 16, v80
	v_sub_f32_e32 v208, 1.0, v207
	v_mul_f32_e32 v207, 0x3fb8aa3b, v218
	v_exp_f32_e32 v207, v207
	v_add_f32_e32 v206, v218, v24
	v_mul_f32_e32 v228, v209, v207
	v_mul_f32_e32 v206, 0x3fb8aa3b, v206
	v_exp_f32_e32 v206, v206
	v_sub_f32_e32 v207, v205, v218
	v_mul_f32_e32 v64, v209, v206
	v_mul_f32_e32 v207, 0x3fb8aa3b, v207
	v_exp_f32_e32 v207, v207
	v_min_f32_e64 v206, -v218, s29
	v_mul_f32_e32 v214, v208, v207
	v_mul_f32_e32 v206, 0x3fb8aa3b, v206
	v_exp_f32_e32 v206, v206
	s_nop 0
	v_mul_f32_e32 v236, v208, v206
	v_add_f32_e32 v218, v204, v73
	v_mul_f32_e32 v207, 0x3fb8aa3b, v65
	v_exp_f32_e32 v207, v207
	v_lshlrev_b32_e32 v209, 16, v81
	v_sub_f32_e32 v208, 1.0, v207
	v_mul_f32_e32 v207, 0x3fb8aa3b, v218
	v_exp_f32_e32 v207, v207
	v_add_f32_e32 v206, v218, v24
	v_mul_f32_e32 v229, v209, v207
	v_mul_f32_e32 v206, 0x3fb8aa3b, v206
	v_exp_f32_e32 v206, v206
	v_sub_f32_e32 v207, v205, v218
	v_mul_f32_e32 v65, v209, v206
	v_mul_f32_e32 v207, 0x3fb8aa3b, v207
	v_exp_f32_e32 v207, v207
	v_min_f32_e64 v206, -v218, s29
	v_mul_f32_e32 v215, v208, v207
	v_mul_f32_e32 v206, 0x3fb8aa3b, v206
	v_exp_f32_e32 v206, v206
	s_nop 0
	v_mul_f32_e32 v237, v208, v206
	v_add_f32_e32 v218, v204, v74
	v_mul_f32_e32 v207, 0x3fb8aa3b, v66
	v_exp_f32_e32 v207, v207
	v_lshlrev_b32_e32 v209, 16, v82
	v_sub_f32_e32 v208, 1.0, v207
	v_mul_f32_e32 v207, 0x3fb8aa3b, v218
	v_exp_f32_e32 v207, v207
	v_add_f32_e32 v206, v218, v24
	v_mul_f32_e32 v230, v209, v207
	v_mul_f32_e32 v206, 0x3fb8aa3b, v206
	v_exp_f32_e32 v206, v206
	v_sub_f32_e32 v207, v205, v218
	v_mul_f32_e32 v66, v209, v206
	v_mul_f32_e32 v207, 0x3fb8aa3b, v207
	v_exp_f32_e32 v207, v207
	v_min_f32_e64 v206, -v218, s29
	v_mul_f32_e32 v216, v208, v207
	v_mul_f32_e32 v206, 0x3fb8aa3b, v206
	v_exp_f32_e32 v206, v206
	s_nop 0
	v_mul_f32_e32 v238, v208, v206
	v_add_f32_e32 v218, v204, v75
	v_mul_f32_e32 v207, 0x3fb8aa3b, v67
	v_exp_f32_e32 v207, v207
	v_lshlrev_b32_e32 v209, 16, v83
	v_sub_f32_e32 v208, 1.0, v207
	v_mul_f32_e32 v207, 0x3fb8aa3b, v218
	v_exp_f32_e32 v207, v207
	v_add_f32_e32 v206, v218, v24
	v_mul_f32_e32 v231, v209, v207
	v_mul_f32_e32 v206, 0x3fb8aa3b, v206
	v_exp_f32_e32 v206, v206
	v_sub_f32_e32 v207, v205, v218
	v_mul_f32_e32 v67, v209, v206
	v_mul_f32_e32 v207, 0x3fb8aa3b, v207
	v_exp_f32_e32 v207, v207
	v_min_f32_e64 v206, -v218, s29
	v_mul_f32_e32 v217, v208, v207
	v_mul_f32_e32 v206, 0x3fb8aa3b, v206
	v_exp_f32_e32 v206, v206
	s_nop 0
	v_mul_f32_e32 v239, v208, v206
	v_cvt_pk_bf16_f32 v224, v224, v225
	ds_write_b16 v2, v224
	ds_write_b16_d16_hi v2, v224 offset:272
	v_cvt_pk_bf16_f32 v232, v232, v233
	ds_write_b16 v2, v232 offset:8704
	ds_write_b16_d16_hi v2, v232 offset:8976
	v_cvt_pk_bf16_f32 v226, v226, v227
	ds_write_b16 v2, v226 offset:544
	ds_write_b16_d16_hi v2, v226 offset:816
	v_cvt_pk_bf16_f32 v234, v234, v235
	ds_write_b16 v2, v234 offset:9248
	ds_write_b16_d16_hi v2, v234 offset:9520
	v_cvt_pk_bf16_f32 v228, v228, v229
	ds_write_b16 v2, v228 offset:1088
	ds_write_b16_d16_hi v2, v228 offset:1360
	v_cvt_pk_bf16_f32 v236, v236, v237
	ds_write_b16 v2, v236 offset:9792
	ds_write_b16_d16_hi v2, v236 offset:10064
	v_cvt_pk_bf16_f32 v230, v230, v231
	ds_write_b16 v2, v230 offset:1632
	ds_write_b16_d16_hi v2, v230 offset:1904
	v_cvt_pk_bf16_f32 v238, v238, v239
	ds_write_b16 v2, v238 offset:10336
	ds_write_b16_d16_hi v2, v238 offset:10608
	v_cvt_pk_bf16_f32 v210, v210, v211
	v_cvt_pk_bf16_f32 v211, v212, v213
	v_cvt_pk_bf16_f32 v212, v214, v215
	v_cvt_pk_bf16_f32 v213, v216, v217
	ds_write_b128 v4, v[210:213] offset:17408
	v_cvt_pk_bf16_f32 v60, v60, v61
	v_cvt_pk_bf16_f32 v62, v62, v63
	v_cvt_pk_bf16_f32 v64, v64, v65
	v_cvt_pk_bf16_f32 v66, v66, v67
	global_store_short v18, v60, s[12:13]
	global_store_short_d16_hi v18, v60, s[12:13] offset:1536
	global_store_short v18, v62, s[12:13] offset:3072
	global_store_short_d16_hi v19, v62, s[12:13]
	global_store_short v19, v64, s[12:13] offset:1536
	global_store_short_d16_hi v19, v64, s[12:13] offset:3072
	global_store_short v20, v66, s[12:13]
	global_store_short_d16_hi v20, v66, s[12:13] offset:1536
	s_add_u32 s12, s12, 0xc000
	s_addc_u32 s13, s13, 0
	s_cmp_gt_u32 s18, 1
	s_cbranch_scc1 .Lhg_w01_5
	v_mul_f32_e32 v207, 0x3fb8aa3b, v205
	v_exp_f32_e32 v207, v207
	s_nop 0
	ds_write_b32 v26, v207 offset:37888

.Lhg_bfirst_3:
	ds_read_b32 v200, v0 offset:57344
	ds_read_b32 v201, v0 offset:57856
	ds_read_b32 v202, v0 offset:58368
	ds_read_b32 v203, v0 offset:58880
	v_lshl_or_b32 v220, v85, 16, v84
	v_lshl_or_b32 v221, v87, 16, v86
	v_lshl_or_b32 v222, v89, 16, v88
	v_lshl_or_b32 v223, v91, 16, v90
	ds_write_b128 v4, v[220:223] offset:27648
	s_waitcnt lgkmcnt(1)
	v_mul_f32_e32 v204, v21, v200
	v_fmac_f32_e32 v204, v22, v201
	v_fmac_f32_e32 v204, v23, v202
	v_add_f32_e32 v205, v200, v201
	v_add_f32_e32 v205, v205, v202
	v_add_f32_e32 v205, v205, v203
	v_add_f32_e32 v218, v204, v68
	v_mul_f32_e32 v207, 0x3fb8aa3b, v60
	v_exp_f32_e32 v207, v207
	v_lshlrev_b32_e32 v209, 16, v76
	v_sub_f32_e32 v208, 1.0, v207
	v_mul_f32_e32 v207, 0x3fb8aa3b, v218
	v_exp_f32_e32 v207, v207
	v_add_f32_e32 v206, v218, v24
	v_mul_f32_e32 v224, v209, v207
	v_mul_f32_e32 v206, 0x3fb8aa3b, v206
	v_exp_f32_e32 v206, v206
	v_sub_f32_e32 v207, v205, v218
	v_mul_f32_e32 v60, v209, v206
	v_mul_f32_e32 v207, 0x3fb8aa3b, v207
	v_exp_f32_e32 v207, v207
	v_min_f32_e64 v206, -v218, s29
	v_mul_f32_e32 v210, v208, v207
	v_mul_f32_e32 v206, 0x3fb8aa3b, v206
	v_exp_f32_e32 v206, v206
	s_nop 0
	v_mul_f32_e32 v232, v208, v206
	v_add_f32_e32 v218, v204, v69
	v_mul_f32_e32 v207, 0x3fb8aa3b, v61
	v_exp_f32_e32 v207, v207
	v_lshlrev_b32_e32 v209, 16, v77
	v_sub_f32_e32 v208, 1.0, v207
	v_mul_f32_e32 v207, 0x3fb8aa3b, v218
	v_exp_f32_e32 v207, v207
	v_add_f32_e32 v206, v218, v24
	v_mul_f32_e32 v225, v209, v207
	v_mul_f32_e32 v206, 0x3fb8aa3b, v206
	v_exp_f32_e32 v206, v206
	v_sub_f32_e32 v207, v205, v218
	v_mul_f32_e32 v61, v209, v206
	v_mul_f32_e32 v207, 0x3fb8aa3b, v207
	v_exp_f32_e32 v207, v207
	v_min_f32_e64 v206, -v218, s29
	v_mul_f32_e32 v211, v208, v207
	v_mul_f32_e32 v206, 0x3fb8aa3b, v206
	v_exp_f32_e32 v206, v206
	s_nop 0
	v_mul_f32_e32 v233, v208, v206
	v_add_f32_e32 v218, v204, v70
	v_mul_f32_e32 v207, 0x3fb8aa3b, v62
	v_exp_f32_e32 v207, v207
	v_lshlrev_b32_e32 v209, 16, v78
	v_sub_f32_e32 v208, 1.0, v207
	v_mul_f32_e32 v207, 0x3fb8aa3b, v218
	v_exp_f32_e32 v207, v207
	v_add_f32_e32 v206, v218, v24
	v_mul_f32_e32 v226, v209, v207
	v_mul_f32_e32 v206, 0x3fb8aa3b, v206
	v_exp_f32_e32 v206, v206
	v_sub_f32_e32 v207, v205, v218
	v_mul_f32_e32 v62, v209, v206
	v_mul_f32_e32 v207, 0x3fb8aa3b, v207
	v_exp_f32_e32 v207, v207
	v_min_f32_e64 v206, -v218, s29
	v_mul_f32_e32 v212, v208, v207
	v_mul_f32_e32 v206, 0x3fb8aa3b, v206
	v_exp_f32_e32 v206, v206
	s_nop 0
	v_mul_f32_e32 v234, v208, v206
	v_add_f32_e32 v218, v204, v71
	v_mul_f32_e32 v207, 0x3fb8aa3b, v63
	v_exp_f32_e32 v207, v207
	v_lshlrev_b32_e32 v209, 16, v79
	v_sub_f32_e32 v208, 1.0, v207
	v_mul_f32_e32 v207, 0x3fb8aa3b, v218
	v_exp_f32_e32 v207, v207
	v_add_f32_e32 v206, v218, v24
	v_mul_f32_e32 v227, v209, v207
	v_mul_f32_e32 v206, 0x3fb8aa3b, v206
	v_exp_f32_e32 v206, v206
	v_sub_f32_e32 v207, v205, v218
	v_mul_f32_e32 v63, v209, v206
	v_mul_f32_e32 v207, 0x3fb8aa3b, v207
	v_exp_f32_e32 v207, v207
	v_min_f32_e64 v206, -v218, s29
	v_mul_f32_e32 v213, v208, v207
	v_mul_f32_e32 v206, 0x3fb8aa3b, v206
	v_exp_f32_e32 v206, v206
	s_nop 0
	v_mul_f32_e32 v235, v208, v206
	v_add_f32_e32 v218, v204, v72
	v_mul_f32_e32 v207, 0x3fb8aa3b, v64
	v_exp_f32_e32 v207, v207
	v_lshlrev_b32_e32 v209, 16, v80
	v_sub_f32_e32 v208, 1.0, v207
	v_mul_f32_e32 v207, 0x3fb8aa3b, v218
	v_exp_f32_e32 v207, v207
	v_add_f32_e32 v206, v218, v24
	v_mul_f32_e32 v228, v209, v207
	v_mul_f32_e32 v206, 0x3fb8aa3b, v206
	v_exp_f32_e32 v206, v206
	v_sub_f32_e32 v207, v205, v218
	v_mul_f32_e32 v64, v209, v206
	v_mul_f32_e32 v207, 0x3fb8aa3b, v207
	v_exp_f32_e32 v207, v207
	v_min_f32_e64 v206, -v218, s29
	v_mul_f32_e32 v214, v208, v207
	v_mul_f32_e32 v206, 0x3fb8aa3b, v206
	v_exp_f32_e32 v206, v206
	s_nop 0
	v_mul_f32_e32 v236, v208, v206
	v_add_f32_e32 v218, v204, v73
	v_mul_f32_e32 v207, 0x3fb8aa3b, v65
	v_exp_f32_e32 v207, v207
	v_lshlrev_b32_e32 v209, 16, v81
	v_sub_f32_e32 v208, 1.0, v207
	v_mul_f32_e32 v207, 0x3fb8aa3b, v218
	v_exp_f32_e32 v207, v207
	v_add_f32_e32 v206, v218, v24
	v_mul_f32_e32 v229, v209, v207
	v_mul_f32_e32 v206, 0x3fb8aa3b, v206
	v_exp_f32_e32 v206, v206
	v_sub_f32_e32 v207, v205, v218
	v_mul_f32_e32 v65, v209, v206
	v_mul_f32_e32 v207, 0x3fb8aa3b, v207
	v_exp_f32_e32 v207, v207
	v_min_f32_e64 v206, -v218, s29
	v_mul_f32_e32 v215, v208, v207
	v_mul_f32_e32 v206, 0x3fb8aa3b, v206
	v_exp_f32_e32 v206, v206
	s_nop 0
	v_mul_f32_e32 v237, v208, v206
	v_add_f32_e32 v218, v204, v74
	v_mul_f32_e32 v207, 0x3fb8aa3b, v66
	v_exp_f32_e32 v207, v207
	v_lshlrev_b32_e32 v209, 16, v82
	v_sub_f32_e32 v208, 1.0, v207
	v_mul_f32_e32 v207, 0x3fb8aa3b, v218
	v_exp_f32_e32 v207, v207
	v_add_f32_e32 v206, v218, v24
	v_mul_f32_e32 v230, v209, v207
	v_mul_f32_e32 v206, 0x3fb8aa3b, v206
	v_exp_f32_e32 v206, v206
	v_sub_f32_e32 v207, v205, v218
	v_mul_f32_e32 v66, v209, v206
	v_mul_f32_e32 v207, 0x3fb8aa3b, v207
	v_exp_f32_e32 v207, v207
	v_min_f32_e64 v206, -v218, s29
	v_mul_f32_e32 v216, v208, v207
	v_mul_f32_e32 v206, 0x3fb8aa3b, v206
	v_exp_f32_e32 v206, v206
	s_nop 0
	v_mul_f32_e32 v238, v208, v206
	v_add_f32_e32 v218, v204, v75
	v_mul_f32_e32 v207, 0x3fb8aa3b, v67
	v_exp_f32_e32 v207, v207
	v_lshlrev_b32_e32 v209, 16, v83
	v_sub_f32_e32 v208, 1.0, v207
	v_mul_f32_e32 v207, 0x3fb8aa3b, v218
	v_exp_f32_e32 v207, v207
	v_add_f32_e32 v206, v218, v24
	v_mul_f32_e32 v231, v209, v207
	v_mul_f32_e32 v206, 0x3fb8aa3b, v206
	v_exp_f32_e32 v206, v206
	v_sub_f32_e32 v207, v205, v218
	v_mul_f32_e32 v67, v209, v206
	v_mul_f32_e32 v207, 0x3fb8aa3b, v207
	v_exp_f32_e32 v207, v207
	v_min_f32_e64 v206, -v218, s29
	v_mul_f32_e32 v217, v208, v207
	v_mul_f32_e32 v206, 0x3fb8aa3b, v206
	v_exp_f32_e32 v206, v206
	s_nop 0
	v_mul_f32_e32 v239, v208, v206
	v_cvt_pk_bf16_f32 v224, v224, v225
	ds_write_b16 v2, v224
	ds_write_b16_d16_hi v2, v224 offset:272
	v_cvt_pk_bf16_f32 v232, v232, v233
	ds_write_b16 v2, v232 offset:8704
	ds_write_b16_d16_hi v2, v232 offset:8976
	v_cvt_pk_bf16_f32 v226, v226, v227
	ds_write_b16 v2, v226 offset:544
	ds_write_b16_d16_hi v2, v226 offset:816
	v_cvt_pk_bf16_f32 v234, v234, v235
	ds_write_b16 v2, v234 offset:9248
	ds_write_b16_d16_hi v2, v234 offset:9520
	v_cvt_pk_bf16_f32 v228, v228, v229
	ds_write_b16 v2, v228 offset:1088
	ds_write_b16_d16_hi v2, v228 offset:1360
	v_cvt_pk_bf16_f32 v236, v236, v237
	ds_write_b16 v2, v236 offset:9792
	ds_write_b16_d16_hi v2, v236 offset:10064
	v_cvt_pk_bf16_f32 v230, v230, v231
	ds_write_b16 v2, v230 offset:1632
	ds_write_b16_d16_hi v2, v230 offset:1904
	v_cvt_pk_bf16_f32 v238, v238, v239
	ds_write_b16 v2, v238 offset:10336
	ds_write_b16_d16_hi v2, v238 offset:10608
	v_cvt_pk_bf16_f32 v210, v210, v211
	v_cvt_pk_bf16_f32 v211, v212, v213
	v_cvt_pk_bf16_f32 v212, v214, v215
	v_cvt_pk_bf16_f32 v213, v216, v217
	ds_write_b128 v4, v[210:213] offset:17408
	v_cvt_pk_bf16_f32 v60, v60, v61
	v_cvt_pk_bf16_f32 v62, v62, v63
	v_cvt_pk_bf16_f32 v64, v64, v65
	v_cvt_pk_bf16_f32 v66, v66, v67
	global_store_short v18, v60, s[12:13]
	global_store_short_d16_hi v18, v60, s[12:13] offset:1536
	global_store_short v18, v62, s[12:13] offset:3072
	global_store_short_d16_hi v19, v62, s[12:13]
	global_store_short v19, v64, s[12:13] offset:1536
	global_store_short_d16_hi v19, v64, s[12:13] offset:3072
	global_store_short v20, v66, s[12:13]
	global_store_short_d16_hi v20, v66, s[12:13] offset:1536
	s_add_u32 s12, s12, 0xc000
	s_addc_u32 s13, s13, 0
	s_cmp_gt_u32 s18, 1
	s_cbranch_scc1 .Lhg_w01_6
	v_mul_f32_e32 v207, 0x3fb8aa3b, v205
	v_exp_f32_e32 v207, v207
	s_nop 0
	ds_write_b32 v26, v207 offset:37888

.Lhg_joined_4:
	s_cmp_gt_u32 s28, 29
	s_cbranch_scc1 .Lhg_nop1_7
	s_waitcnt vmcnt(8)
	v_mov_b32_e32 v36, v28
	v_add_f32_e32 v37, v36, v29
	v_add_f32_e32 v38, v37, v30
	v_add_f32_e32 v39, v38, v31
	v_add_f32_e32 v40, v39, v32
	v_add_f32_e32 v41, v40, v33
	v_add_f32_e32 v42, v41, v34
	v_add_f32_e32 v43, v42, v35
	ds_write_b32 v1, v43
.Lhg_nop1_7:
	s_waitcnt lgkmcnt(0)
	s_barrier
	ds_read_b128 v[200:203], v12
	ds_read_b128 v[204:207], v12 offset:16
	s_waitcnt lgkmcnt(0)
	v_cvt_pk_bf16_f32 v200, v200, v201
	v_cvt_pk_bf16_f32 v201, v202, v203
	v_cvt_pk_bf16_f32 v202, v204, v205
	v_cvt_pk_bf16_f32 v203, v206, v207
	global_store_dwordx4 v13, v[200:203], s[14:15]
	s_add_u32 s14, s14, 0x10000
	s_addc_u32 s15, s15, 0
	v_xor_b32_e32 v2, 0x10000, v2
	v_xor_b32_e32 v4, 0x10000, v4
	v_xor_b32_e32 v26, 0x10000, v26
	v_xor_b32_e32 v5, 0x10000, v5
	v_xor_b32_e32 v6, 0x10000, v6
	v_xor_b32_e32 v7, 0x10000, v7
	v_xor_b32_e32 v8, 0x10000, v8
	v_xor_b32_e32 v9, 0x10000, v9
	v_xor_b32_e32 v10, 0x10000, v10
	v_xor_b32_e32 v11, 0x10000, v11
	v_xor_b32_e32 v12, 0x10000, v12
	s_add_i32 s28, s28, 1
	s_cmp_eq_u32 s28, 31
	s_cbranch_scc1 .Lhg_last
	s_cmp_gt_u32 s28, 29
	s_cbranch_scc1 .Lhg_noload_8
	global_load_dword v60, v14, s[4:5]
	global_load_dword v61, v14, s[4:5] offset:3072
	global_load_dword v62, v15, s[4:5]
	global_load_dword v63, v15, s[4:5] offset:3072
	global_load_dword v64, v16, s[4:5]
	global_load_dword v65, v16, s[4:5] offset:3072
	global_load_dword v66, v17, s[4:5]
	global_load_dword v67, v17, s[4:5] offset:3072
	global_load_ushort v76, v18, s[8:9]
	global_load_ushort v77, v18, s[8:9] offset:1536
	global_load_ushort v78, v18, s[8:9] offset:3072
	global_load_ushort v79, v19, s[8:9]
	global_load_ushort v80, v19, s[8:9] offset:1536
	global_load_ushort v81, v19, s[8:9] offset:3072
	global_load_ushort v82, v20, s[8:9]
	global_load_ushort v83, v20, s[8:9] offset:1536
	global_load_ushort v84, v18, s[10:11]
	global_load_ushort v85, v18, s[10:11] offset:1536
	global_load_ushort v86, v18, s[10:11] offset:3072
	global_load_ushort v87, v19, s[10:11]
	global_load_ushort v88, v19, s[10:11] offset:1536
	global_load_ushort v89, v19, s[10:11] offset:3072
	global_load_ushort v90, v20, s[10:11]
	global_load_ushort v91, v20, s[10:11] offset:1536
	s_add_u32 s4, s4, 0x18000
	s_addc_u32 s5, s5, 0
	s_add_u32 s8, s8, 0xc000
	s_addc_u32 s9, s9, 0
	s_add_u32 s10, s10, 0xc000
	s_addc_u32 s11, s11, 0

.Lhg_joined_10:
	s_cmp_gt_u32 s28, 29
	s_cbranch_scc1 .Lhg_nop1_13
	s_waitcnt vmcnt(8)
	v_mov_b32_e32 v68, v60
	v_add_f32_e32 v69, v68, v61
	v_add_f32_e32 v70, v69, v62
	v_add_f32_e32 v71, v70, v63
	v_add_f32_e32 v72, v71, v64
	v_add_f32_e32 v73, v72, v65
	v_add_f32_e32 v74, v73, v66
	v_add_f32_e32 v75, v74, v67
	ds_write_b32 v1, v75 offset:2048
.Lhg_nop1_13:
	s_waitcnt lgkmcnt(0)
	s_barrier
	ds_read_b128 v[200:203], v12
	ds_read_b128 v[204:207], v12 offset:16
	s_waitcnt lgkmcnt(0)
	v_cvt_pk_bf16_f32 v200, v200, v201
	v_cvt_pk_bf16_f32 v201, v202, v203
	v_cvt_pk_bf16_f32 v202, v204, v205
	v_cvt_pk_bf16_f32 v203, v206, v207
	global_store_dwordx4 v13, v[200:203], s[14:15]
	s_add_u32 s14, s14, 0x10000
	s_addc_u32 s15, s15, 0
	v_xor_b32_e32 v2, 0x10000, v2
	v_xor_b32_e32 v4, 0x10000, v4
	v_xor_b32_e32 v26, 0x10000, v26
	v_xor_b32_e32 v5, 0x10000, v5
	v_xor_b32_e32 v6, 0x10000, v6
	v_xor_b32_e32 v7, 0x10000, v7
	v_xor_b32_e32 v8, 0x10000, v8
	v_xor_b32_e32 v9, 0x10000, v9
	v_xor_b32_e32 v10, 0x10000, v10
	v_xor_b32_e32 v11, 0x10000, v11
	v_xor_b32_e32 v12, 0x10000, v12
	s_add_i32 s28, s28, 1
	s_branch .Lhg_loop
